# attention inner loop (diff+MLA) rewritten: 2 QK chains, -m folded into MFMA C, deep K/V frag prefetch, max3 tree
# speedup vs baseline: 1.0358x; 1.0358x over previous
.LBB0_106:
	v_mov_b32_e32 v14, v0
	v_mov_b32_e32 v15, v0
	s_waitcnt vmcnt(0) lgkmcnt(0)
	s_barrier
	v_mov_b32_e32 v1, v0
	v_mov_b32_e32 v2, v0
	v_mov_b32_e32 v3, v0
	v_mov_b32_e32 v4, v0
	v_mov_b32_e32 v5, v0
	v_mov_b32_e32 v6, v0
	v_mov_b32_e32 v7, v0
	v_mov_b32_e32 v8, v0
	v_mov_b32_e32 v9, v0
	v_mov_b32_e32 v10, v0
	v_mov_b32_e32 v11, v0
	v_mov_b32_e32 v12, v0
	v_mov_b32_e32 v13, v0
	s_lshl_b32 s30, s43, 12
	s_lshl_b32 s44, s48, 7
	v_mov_b64_e32 v[62:63], v[14:15]
	v_mov_b64_e32 v[46:47], v[14:15]
	v_mov_b64_e32 v[30:31], v[14:15]
	s_add_i32 s43, s30, 0xffffff80
	v_add_u32_e32 v153, s44, v171
	v_add_u32_e32 v155, s44, v172
	s_add_i32 s45, s46, 0x80
	s_mov_b32 s50, 2
	s_mov_b32 s51, 1
	s_mov_b32 s53, 0
	v_mov_b32_e32 v157, 0
	v_mov_b32_e32 v159, 0
	v_mov_b32_e32 v96, 0
	v_mov_b32_e32 v97, 0
	v_mov_b32_e32 v98, 0
	v_mov_b32_e32 v99, 0
	v_mov_b32_e32 v100, 0
	v_mov_b32_e32 v101, 0
	v_mov_b32_e32 v102, 0
	v_mov_b32_e32 v103, 0
	v_mov_b32_e32 v104, 0
	v_mov_b32_e32 v105, 0
	v_mov_b32_e32 v106, 0
	v_mov_b32_e32 v107, 0
	v_mov_b32_e32 v108, 0
	v_mov_b32_e32 v109, 0
	v_mov_b32_e32 v110, 0
	v_mov_b32_e32 v111, 0
	v_mov_b64_e32 v[60:61], v[12:13]
	v_mov_b64_e32 v[58:59], v[10:11]
	v_mov_b64_e32 v[56:57], v[8:9]
	v_mov_b64_e32 v[54:55], v[6:7]
	v_mov_b64_e32 v[52:53], v[4:5]
	v_mov_b64_e32 v[50:51], v[2:3]
	v_mov_b64_e32 v[48:49], v[0:1]
	v_mov_b64_e32 v[44:45], v[12:13]
	v_mov_b64_e32 v[42:43], v[10:11]
	v_mov_b64_e32 v[40:41], v[8:9]
	v_mov_b64_e32 v[38:39], v[6:7]
	v_mov_b64_e32 v[36:37], v[4:5]
	v_mov_b64_e32 v[34:35], v[2:3]
	v_mov_b64_e32 v[32:33], v[0:1]
	v_mov_b64_e32 v[28:29], v[12:13]
	v_mov_b64_e32 v[26:27], v[10:11]
	v_mov_b64_e32 v[24:25], v[8:9]
	v_mov_b64_e32 v[22:23], v[6:7]
	v_mov_b64_e32 v[20:21], v[4:5]
	v_mov_b64_e32 v[18:19], v[2:3]
	v_mov_b64_e32 v[16:17], v[0:1]
	s_mov_b32 s52, 0
	s_waitcnt vmcnt(0)
.LBB0_107:
	s_add_i32 s30, s52, 2
	s_cmp_ge_u32 s30, s21
	s_cselect_b64 s[46:47], -1, 0
	s_and_b64 vcc, exec, s[46:47]
	s_cbranch_vccnz .LBB0_116
	s_cmp_lt_u32 s52, 2
	s_mul_i32 s55, s50, 0x2400
	s_cselect_b32 s48, s45, s43
	s_and_b64 vcc, exec, s[6:7]
	s_add_i32 s56, s55, 0
	s_cbranch_vccnz .LBB0_110
	s_add_i32 m0, s56, s41
	v_lshl_add_u32 v244, s48, 12, v153
	global_load_lds_dwordx4 v244, s[18:19]
.LBB0_110:
	s_and_b64 vcc, exec, s[8:9]
	s_cbranch_vccnz .LBB0_112
	s_add_i32 s30, s56, s41
	s_add_i32 m0, s30, 0x2000
	v_lshl_add_u32 v244, s48, 12, v155
	global_load_lds_dwordx4 v244, s[18:19]
.LBB0_112:
	s_ashr_i32 s49, s48, 31
	s_lshl_b64 s[30:31], s[48:49], 1
	s_add_u32 s48, s39, s30
	s_addc_u32 s49, s42, s31
	s_and_b64 vcc, exec, s[10:11]
	s_add_i32 s55, s56, s55
	s_cbranch_vccnz .LBB0_124
	s_add_i32 s30, s55, s41
	s_add_i32 m0, s30, 0x6c00
	v_lshl_add_u64 v[244:245], s[48:49], 0, v[150:151]
	global_load_lds_dwordx4 v[244:245], off
	s_and_b64 vcc, exec, s[12:13]
	s_cbranch_vccz .LBB0_125

.LBB0_115:
	s_add_i32 s30, s55, s41
	s_add_i32 m0, s30, 0xac00
	v_lshl_add_u64 v[244:245], s[48:49], 0, v[146:147]
	global_load_lds_dwordx4 v[244:245], off
.LBB0_116:
	s_mul_i32 s30, s53, 0x2400
	v_add_u32_e32 v242, s30, v173
	ds_read_b128 v[112:115], v242 offset:0
	ds_read_b128 v[116:119], v242 offset:4608
	ds_read_b128 v[120:123], v242 offset:32
	ds_read_b128 v[124:127], v242 offset:4640
	ds_read_b128 v[202:205], v242 offset:64
	ds_read_b128 v[206:209], v242 offset:4672
	ds_read_b128 v[210:213], v242 offset:96
	ds_read_b128 v[214:217], v242 offset:4704
	s_mul_i32 s30, s53, 0x4800
	v_add_u32_e32 v243, s30, v174
	s_waitcnt lgkmcnt(7)
	v_mfma_f32_32x32x16_bf16 v[64:79], v[112:115], v[130:133], v[96:111]
	s_waitcnt lgkmcnt(6)
	v_mfma_f32_32x32x16_bf16 v[80:95], v[116:119], v[130:133], v[96:111]
	s_waitcnt lgkmcnt(5)
	v_mfma_f32_32x32x16_bf16 v[64:79], v[120:123], v[134:137], v[64:79]
	s_waitcnt lgkmcnt(4)
	v_mfma_f32_32x32x16_bf16 v[80:95], v[124:127], v[134:137], v[80:95]
	s_waitcnt lgkmcnt(3)
	v_mfma_f32_32x32x16_bf16 v[64:79], v[202:205], v[138:141], v[64:79]
	s_waitcnt lgkmcnt(2)
	v_mfma_f32_32x32x16_bf16 v[80:95], v[206:209], v[138:141], v[80:95]
	s_waitcnt lgkmcnt(1)
	v_mfma_f32_32x32x16_bf16 v[64:79], v[210:213], v[142:145], v[64:79]
	s_waitcnt lgkmcnt(0)
	v_mfma_f32_32x32x16_bf16 v[80:95], v[214:217], v[142:145], v[80:95]
	ds_read_b128 v[112:115], v243 offset:27648
	ds_read_b128 v[116:119], v243 offset:32256
	ds_read_b128 v[120:123], v243 offset:36864
	ds_read_b128 v[124:127], v243 offset:41472
	ds_read_b128 v[202:205], v243 offset:27680
	ds_read_b128 v[206:209], v243 offset:32288
	ds_read_b128 v[210:213], v243 offset:36896
	ds_read_b128 v[214:217], v243 offset:41504
	s_cmp_eq_u32 s52, 0
	s_cselect_b32 s31, 0xff7fffff, 0
	s_nop 0
	v_max3_f32 v226, v64, v65, v66
	v_max3_f32 v227, v67, v68, v69
	v_max3_f32 v226, v226, v70, v71
	v_max3_f32 v227, v227, v72, v73
	v_max3_f32 v226, v226, v74, v75
	v_max3_f32 v227, v227, v76, v77
	v_max3_f32 v226, v226, v78, v79
	v_max3_f32 v228, v80, v81, v82
	v_max3_f32 v229, v83, v84, v85
	v_max3_f32 v228, v228, v86, v87
	v_max3_f32 v229, v229, v88, v89
	v_max3_f32 v228, v228, v90, v91
	v_max3_f32 v229, v229, v92, v93
	v_max3_f32 v228, v228, v94, v95
	v_max3_f32 v226, v226, v227, v228
	v_max_f32_e32 v226, v226, v229
	v_mov_b32_e32 v227, v226
	s_nop 1
	v_permlane32_swap_b32_e32 v226, v227
	v_max_f32_e32 v237, v226, v227
	v_cmp_lt_f32_e32 vcc, s58, v237
	s_cmp_eq_u32 s52, 0
	s_cbranch_scc1 .Latt_diff_rare
	s_cbranch_vccz .Latt_diff_norescale
.Latt_diff_rare:
	v_max_f32_e32 v238, s31, v237
	v_max_f32_e32 v239, 0, v238
	v_add_f32_e32 v159, v159, v238
	v_exp_f32_e64 v240, -v239
	v_sub_f32_e32 v96, v96, v238
	v_mov_b32_e32 v97, v96
	v_mov_b32_e32 v98, v96
	v_mov_b32_e32 v99, v96
	v_mov_b32_e32 v100, v96
	v_mov_b32_e32 v101, v96
	v_mov_b32_e32 v102, v96
	v_mov_b32_e32 v103, v96
	v_mov_b32_e32 v104, v96
	v_mov_b32_e32 v105, v96
	v_mov_b32_e32 v106, v96
	v_mov_b32_e32 v107, v96
	v_mov_b32_e32 v108, v96
	v_mov_b32_e32 v109, v96
	v_mov_b32_e32 v110, v96
	v_mov_b32_e32 v111, v96
	v_sub_f32_e32 v64, v64, v238
	v_sub_f32_e32 v65, v65, v238
	v_sub_f32_e32 v66, v66, v238
	v_sub_f32_e32 v67, v67, v238
	v_sub_f32_e32 v68, v68, v238
	v_sub_f32_e32 v69, v69, v238
	v_sub_f32_e32 v70, v70, v238
	v_sub_f32_e32 v71, v71, v238
	v_sub_f32_e32 v72, v72, v238
	v_sub_f32_e32 v73, v73, v238
	v_sub_f32_e32 v74, v74, v238
	v_sub_f32_e32 v75, v75, v238
	v_sub_f32_e32 v76, v76, v238
	v_sub_f32_e32 v77, v77, v238
	v_sub_f32_e32 v78, v78, v238
	v_sub_f32_e32 v79, v79, v238
	v_sub_f32_e32 v80, v80, v238
	v_sub_f32_e32 v81, v81, v238
	v_sub_f32_e32 v82, v82, v238
	v_sub_f32_e32 v83, v83, v238
	v_sub_f32_e32 v84, v84, v238
	v_sub_f32_e32 v85, v85, v238
	v_sub_f32_e32 v86, v86, v238
	v_sub_f32_e32 v87, v87, v238
	v_sub_f32_e32 v88, v88, v238
	v_sub_f32_e32 v89, v89, v238
	v_sub_f32_e32 v90, v90, v238
	v_sub_f32_e32 v91, v91, v238
	v_sub_f32_e32 v92, v92, v238
	v_sub_f32_e32 v93, v93, v238
	v_sub_f32_e32 v94, v94, v238
	v_sub_f32_e32 v95, v95, v238
	v_mul_f32_e32 v157, v157, v240
	v_pk_mul_f32 v[0:1], v[0:1], v[240:241] op_sel_hi:[1,0]
	v_pk_mul_f32 v[2:3], v[2:3], v[240:241] op_sel_hi:[1,0]
	v_pk_mul_f32 v[4:5], v[4:5], v[240:241] op_sel_hi:[1,0]
	v_pk_mul_f32 v[6:7], v[6:7], v[240:241] op_sel_hi:[1,0]
	v_pk_mul_f32 v[8:9], v[8:9], v[240:241] op_sel_hi:[1,0]
	v_pk_mul_f32 v[10:11], v[10:11], v[240:241] op_sel_hi:[1,0]
	v_pk_mul_f32 v[12:13], v[12:13], v[240:241] op_sel_hi:[1,0]
	v_pk_mul_f32 v[14:15], v[14:15], v[240:241] op_sel_hi:[1,0]
	v_pk_mul_f32 v[48:49], v[48:49], v[240:241] op_sel_hi:[1,0]
	v_pk_mul_f32 v[50:51], v[50:51], v[240:241] op_sel_hi:[1,0]
	v_pk_mul_f32 v[52:53], v[52:53], v[240:241] op_sel_hi:[1,0]
	v_pk_mul_f32 v[54:55], v[54:55], v[240:241] op_sel_hi:[1,0]
	v_pk_mul_f32 v[56:57], v[56:57], v[240:241] op_sel_hi:[1,0]
	v_pk_mul_f32 v[58:59], v[58:59], v[240:241] op_sel_hi:[1,0]
	v_pk_mul_f32 v[60:61], v[60:61], v[240:241] op_sel_hi:[1,0]
	v_pk_mul_f32 v[62:63], v[62:63], v[240:241] op_sel_hi:[1,0]
	v_pk_mul_f32 v[32:33], v[32:33], v[240:241] op_sel_hi:[1,0]
	v_pk_mul_f32 v[34:35], v[34:35], v[240:241] op_sel_hi:[1,0]
	v_pk_mul_f32 v[36:37], v[36:37], v[240:241] op_sel_hi:[1,0]
	v_pk_mul_f32 v[38:39], v[38:39], v[240:241] op_sel_hi:[1,0]
	v_pk_mul_f32 v[40:41], v[40:41], v[240:241] op_sel_hi:[1,0]
	v_pk_mul_f32 v[42:43], v[42:43], v[240:241] op_sel_hi:[1,0]
	v_pk_mul_f32 v[44:45], v[44:45], v[240:241] op_sel_hi:[1,0]
	v_pk_mul_f32 v[46:47], v[46:47], v[240:241] op_sel_hi:[1,0]
	v_pk_mul_f32 v[16:17], v[16:17], v[240:241] op_sel_hi:[1,0]
	v_pk_mul_f32 v[18:19], v[18:19], v[240:241] op_sel_hi:[1,0]
	v_pk_mul_f32 v[20:21], v[20:21], v[240:241] op_sel_hi:[1,0]
	v_pk_mul_f32 v[22:23], v[22:23], v[240:241] op_sel_hi:[1,0]
	v_pk_mul_f32 v[24:25], v[24:25], v[240:241] op_sel_hi:[1,0]
	v_pk_mul_f32 v[26:27], v[26:27], v[240:241] op_sel_hi:[1,0]
	v_pk_mul_f32 v[28:29], v[28:29], v[240:241] op_sel_hi:[1,0]
	v_pk_mul_f32 v[30:31], v[30:31], v[240:241] op_sel_hi:[1,0]
.Latt_diff_norescale:
	v_exp_f32_e32 v64, v64
	v_exp_f32_e32 v65, v65
	v_exp_f32_e32 v66, v66
	v_exp_f32_e32 v67, v67
	v_exp_f32_e32 v68, v68
	v_exp_f32_e32 v69, v69
	v_exp_f32_e32 v70, v70
	v_exp_f32_e32 v71, v71
	v_cvt_pk_bf16_f32 v218, v64, v65
	v_cvt_pk_bf16_f32 v219, v66, v67
	v_cvt_pk_bf16_f32 v220, v68, v69
	v_cvt_pk_bf16_f32 v221, v70, v71
	s_waitcnt lgkmcnt(7)
	s_nop 0
	v_mfma_f32_32x32x16_bf16 v[0:15], v[112:115], v[218:221], v[0:15]
	ds_read_b128 v[112:115], v243 offset:27712
	v_exp_f32_e32 v72, v72
	v_exp_f32_e32 v73, v73
	v_exp_f32_e32 v74, v74
	v_exp_f32_e32 v75, v75
	s_waitcnt lgkmcnt(7)
	v_mfma_f32_32x32x16_bf16 v[48:63], v[116:119], v[218:221], v[48:63]
	ds_read_b128 v[116:119], v243 offset:32320
	v_cvt_pk_bf16_f32 v222, v72, v73
	v_exp_f32_e32 v76, v76
	v_exp_f32_e32 v77, v77
	v_cvt_pk_bf16_f32 v223, v74, v75
	s_waitcnt lgkmcnt(7)
	v_mfma_f32_32x32x16_bf16 v[32:47], v[120:123], v[218:221], v[32:47]
	ds_read_b128 v[120:123], v243 offset:36928
	v_exp_f32_e32 v78, v78
	v_exp_f32_e32 v79, v79
	v_cvt_pk_bf16_f32 v224, v76, v77
	v_cvt_pk_bf16_f32 v225, v78, v79
	s_waitcnt lgkmcnt(7)
	v_mfma_f32_32x32x16_bf16 v[16:31], v[124:127], v[218:221], v[16:31]
	ds_read_b128 v[124:127], v243 offset:41536
	v_add_f32_e32 v226, v64, v68
	v_add_f32_e32 v227, v65, v69
	v_add_f32_e32 v228, v66, v70
	v_add_f32_e32 v229, v67, v71
	s_waitcnt lgkmcnt(7)
	v_mfma_f32_32x32x16_bf16 v[0:15], v[202:205], v[222:225], v[0:15]
	ds_read_b128 v[202:205], v243 offset:27744
	v_exp_f32_e32 v80, v80
	v_exp_f32_e32 v81, v81
	v_exp_f32_e32 v82, v82
	v_exp_f32_e32 v83, v83
	v_cvt_pk_bf16_f32 v218, v80, v81
	s_waitcnt lgkmcnt(7)
	v_mfma_f32_32x32x16_bf16 v[48:63], v[206:209], v[222:225], v[48:63]
	ds_read_b128 v[206:209], v243 offset:32352
	v_exp_f32_e32 v84, v84
	v_exp_f32_e32 v85, v85
	v_cvt_pk_bf16_f32 v219, v82, v83
	v_exp_f32_e32 v86, v86
	v_exp_f32_e32 v87, v87
	s_waitcnt lgkmcnt(7)
	v_mfma_f32_32x32x16_bf16 v[32:47], v[210:213], v[222:225], v[32:47]
	ds_read_b128 v[210:213], v243 offset:36960
	v_cvt_pk_bf16_f32 v220, v84, v85
	v_cvt_pk_bf16_f32 v221, v86, v87
	v_add_f32_e32 v226, v226, v72
	v_add_f32_e32 v227, v227, v73
	v_add_f32_e32 v228, v228, v74
	s_waitcnt lgkmcnt(7)
	v_mfma_f32_32x32x16_bf16 v[16:31], v[214:217], v[222:225], v[16:31]
	ds_read_b128 v[214:217], v243 offset:41568
	v_add_f32_e32 v229, v229, v75
	v_add_f32_e32 v226, v226, v76
	v_add_f32_e32 v227, v227, v77
	v_add_f32_e32 v228, v228, v78
	v_add_f32_e32 v229, v229, v79
	s_waitcnt lgkmcnt(7)
	v_mfma_f32_32x32x16_bf16 v[0:15], v[112:115], v[218:221], v[0:15]
	v_exp_f32_e32 v88, v88
	v_exp_f32_e32 v89, v89
	v_exp_f32_e32 v90, v90
	v_exp_f32_e32 v91, v91
	v_cvt_pk_bf16_f32 v222, v88, v89
	s_waitcnt lgkmcnt(6)
	v_mfma_f32_32x32x16_bf16 v[48:63], v[116:119], v[218:221], v[48:63]
	v_exp_f32_e32 v92, v92
	v_exp_f32_e32 v93, v93
	v_cvt_pk_bf16_f32 v223, v90, v91
	v_exp_f32_e32 v94, v94
	v_exp_f32_e32 v95, v95
	s_waitcnt lgkmcnt(5)
	v_mfma_f32_32x32x16_bf16 v[32:47], v[120:123], v[218:221], v[32:47]
	v_cvt_pk_bf16_f32 v224, v92, v93
	v_cvt_pk_bf16_f32 v225, v94, v95
	v_add_f32_e32 v226, v226, v80
	v_add_f32_e32 v227, v227, v81
	v_add_f32_e32 v228, v228, v82
	s_waitcnt lgkmcnt(4)
	v_mfma_f32_32x32x16_bf16 v[16:31], v[124:127], v[218:221], v[16:31]
	v_add_f32_e32 v229, v229, v83
	v_add_f32_e32 v226, v226, v84
	v_add_f32_e32 v227, v227, v85
	v_add_f32_e32 v228, v228, v86
	v_add_f32_e32 v229, v229, v87
	s_waitcnt lgkmcnt(3)
	v_mfma_f32_32x32x16_bf16 v[0:15], v[202:205], v[222:225], v[0:15]
	v_add_f32_e32 v226, v226, v88
	v_add_f32_e32 v227, v227, v89
	s_waitcnt lgkmcnt(2)
	v_mfma_f32_32x32x16_bf16 v[48:63], v[206:209], v[222:225], v[48:63]
	v_add_f32_e32 v228, v228, v90
	v_add_f32_e32 v229, v229, v91
	s_waitcnt lgkmcnt(1)
	v_mfma_f32_32x32x16_bf16 v[32:47], v[210:213], v[222:225], v[32:47]
	v_add_f32_e32 v226, v226, v92
	v_add_f32_e32 v227, v227, v93
	s_waitcnt lgkmcnt(0)
	v_mfma_f32_32x32x16_bf16 v[16:31], v[214:217], v[222:225], v[16:31]
	v_add_f32_e32 v228, v228, v94
	v_add_f32_e32 v229, v229, v95
	v_add_f32_e32 v226, v226, v227
	v_add_f32_e32 v228, v228, v229
	v_add_f32_e32 v226, v226, v228
	v_add_f32_e32 v157, v157, v226
	s_and_b64 vcc, exec, s[46:47]
	s_cbranch_vccz .Latt_diff_w_n
	s_waitcnt vmcnt(0)
	s_branch .Latt_diff_w_d
.Latt_diff_w_n:
	s_waitcnt vmcnt(3)
.Latt_diff_w_d:
	s_waitcnt lgkmcnt(0)
	s_barrier
	s_add_i32 s30, s50, 1
	s_cmp_lg_u32 s50, 2
	s_cselect_b32 s46, s30, 0
	s_add_i32 s52, s52, 1
	s_add_i32 s43, s43, 64
	s_add_i32 s45, s45, 64
	s_cmp_eq_u32 s21, s52
	s_cbranch_scc1 .LBB0_88
	s_mov_b32 s53, s51
	s_mov_b32 s51, s50
	s_mov_b32 s50, s46
	s_branch .LBB0_107

.LBB0_125:
	s_add_i32 s30, s55, s41
	s_add_i32 m0, s30, 0x8c00
	v_lshl_add_u64 v[244:245], s[48:49], 0, v[148:149]
	global_load_lds_dwordx4 v[244:245], off
	s_and_b64 vcc, exec, s[14:15]
	s_cbranch_vccz .LBB0_115
	s_branch .LBB0_116

.LBB0_177:
	v_mov_b32_e32 v14, v0
	v_mov_b32_e32 v15, v0
	s_waitcnt vmcnt(0) lgkmcnt(0)
	s_barrier
	v_mov_b32_e32 v1, v0
	v_mov_b32_e32 v2, v0
	v_mov_b32_e32 v3, v0
	v_mov_b32_e32 v4, v0
	v_mov_b32_e32 v5, v0
	v_mov_b32_e32 v6, v0
	v_mov_b32_e32 v7, v0
	v_mov_b32_e32 v8, v0
	v_mov_b32_e32 v9, v0
	v_mov_b32_e32 v10, v0
	v_mov_b32_e32 v11, v0
	v_mov_b32_e32 v12, v0
	v_mov_b32_e32 v13, v0
	s_lshl_b32 s49, s49, 12
	v_mov_b64_e32 v[30:31], v[14:15]
	v_mov_b64_e32 v[46:47], v[14:15]
	v_mov_b64_e32 v[62:63], v[14:15]
	v_mad_u64_u32 v[222:223], s[30:31], s50, v238, v[190:191]
	v_mad_u64_u32 v[224:225], s[30:31], s50, v240, v[192:193]
	v_mad_u64_u32 v[226:227], s[30:31], s50, v242, v[194:195]
	v_mad_u64_u32 v[228:229], s[30:31], s50, v244, v[196:197]
	s_addk_i32 s49, 0xff80
	s_add_i32 s51, s60, 0x80
	s_mov_b32 s52, 2
	s_mov_b32 s53, 1
	s_mov_b32 s56, 0
	v_mov_b32_e32 v205, 0
	v_mov_b32_e32 v207, 0
	v_mov_b32_e32 v96, 0
	v_mov_b32_e32 v97, 0
	v_mov_b32_e32 v98, 0
	v_mov_b32_e32 v99, 0
	v_mov_b32_e32 v100, 0
	v_mov_b32_e32 v101, 0
	v_mov_b32_e32 v102, 0
	v_mov_b32_e32 v103, 0
	v_mov_b32_e32 v104, 0
	v_mov_b32_e32 v105, 0
	v_mov_b32_e32 v106, 0
	v_mov_b32_e32 v107, 0
	v_mov_b32_e32 v108, 0
	v_mov_b32_e32 v109, 0
	v_mov_b32_e32 v110, 0
	v_mov_b32_e32 v111, 0
	v_mov_b64_e32 v[28:29], v[12:13]
	v_mov_b64_e32 v[26:27], v[10:11]
	v_mov_b64_e32 v[24:25], v[8:9]
	v_mov_b64_e32 v[22:23], v[6:7]
	v_mov_b64_e32 v[20:21], v[4:5]
	v_mov_b64_e32 v[18:19], v[2:3]
	v_mov_b64_e32 v[16:17], v[0:1]
	v_mov_b64_e32 v[44:45], v[12:13]
	v_mov_b64_e32 v[42:43], v[10:11]
	v_mov_b64_e32 v[40:41], v[8:9]
	v_mov_b64_e32 v[38:39], v[6:7]
	v_mov_b64_e32 v[36:37], v[4:5]
	v_mov_b64_e32 v[34:35], v[2:3]
	v_mov_b64_e32 v[32:33], v[0:1]
	v_mov_b64_e32 v[60:61], v[12:13]
	v_mov_b64_e32 v[58:59], v[10:11]
	v_mov_b64_e32 v[56:57], v[8:9]
	v_mov_b64_e32 v[54:55], v[6:7]
	v_mov_b64_e32 v[52:53], v[4:5]
	v_mov_b64_e32 v[50:51], v[2:3]
	v_mov_b64_e32 v[48:49], v[0:1]
	s_mov_b32 s55, 0
	s_waitcnt vmcnt(0)
.LBB0_178:
	s_add_i32 s30, s55, 2
	s_cmp_ge_u32 s30, s20
	s_cselect_b64 s[60:61], -1, 0
	s_and_b64 vcc, exec, s[60:61]
	s_cbranch_vccnz .LBB0_191
	s_cmp_lt_u32 s55, 2
	s_mul_i32 s30, s52, 0x6400
	s_cselect_b32 s62, s51, s49
	s_and_b64 vcc, exec, s[6:7]
	s_add_i32 s57, s30, 0
	s_cbranch_vccnz .LBB0_184
	s_add_i32 m0, s57, s42
	v_mad_u64_u32 v[250:251], s[30:31], s62, v237, v[222:223]
	global_load_lds_dwordx4 v250, s[2:3]
	s_and_b64 vcc, exec, s[8:9]
	s_cbranch_vccz .LBB0_185

.LBB0_182:
	s_add_i32 s30, s57, s42
	s_add_i32 m0, s30, 0x4000
	v_mad_u64_u32 v[250:251], s[30:31], s62, v241, v[226:227]
	global_load_lds_dwordx4 v250, s[2:3]
	s_and_b64 vcc, exec, s[12:13]
	s_cbranch_vccnz .LBB0_187
.LBB0_183:
	s_add_i32 s30, s57, s42
	s_add_i32 m0, s30, 0x6000
	v_mad_u64_u32 v[250:251], s[30:31], s62, v243, v[228:229]
	global_load_lds_dwordx4 v250, s[2:3]
	s_branch .LBB0_187

.LBB0_185:
	s_add_i32 s30, s57, s42
	s_add_i32 m0, s30, 0x2000
	v_mad_u64_u32 v[250:251], s[30:31], s62, v239, v[224:225]
	global_load_lds_dwordx4 v250, s[2:3]
	s_and_b64 vcc, exec, s[10:11]
	s_cbranch_vccz .LBB0_182

.LBB0_187:
	s_ashr_i32 s63, s62, 31
	s_lshl_b64 s[30:31], s[62:63], 1
	s_add_u32 s62, s21, s30
	s_mul_i32 s30, s52, 0x4800
	s_addc_u32 s63, s43, s31
	s_add_i32 s57, s30, 0
	s_and_b64 vcc, exec, s[14:15]
	s_add_i32 s57, s57, 0x12c00
	s_cbranch_vccnz .LBB0_199
	s_add_i32 m0, s57, s42
	v_lshl_add_u64 v[250:251], s[62:63], 0, v[202:203]
	global_load_lds_dwordx4 v[250:251], off
	s_and_b64 vcc, exec, s[16:17]
	s_cbranch_vccz .LBB0_200

.LBB0_190:
	s_add_i32 s30, s57, s42
	s_add_i32 m0, s30, 0x4000
	v_lshl_add_u64 v[250:251], s[62:63], 0, v[198:199]
	global_load_lds_dwordx4 v[250:251], off
.LBB0_191:
	s_mul_i32 s30, s56, 0x6400
	v_add_u32_e32 v209, s30, v246
	ds_read_b128 v[112:115], v209 offset:0
	ds_read_b128 v[116:119], v209 offset:12800
	ds_read_b128 v[120:123], v209 offset:32
	ds_read_b128 v[124:127], v209 offset:12832
	ds_read_b128 v[250:253], v209 offset:64
	s_mul_i32 s30, s56, 0x4800
	v_add_u32_e32 v219, s30, v247
	s_waitcnt lgkmcnt(4)
	v_mfma_f32_32x32x16_bf16 v[64:79], v[112:115], v[130:133], v[96:111]
	ds_read_b128 v[112:115], v209 offset:12864
	s_waitcnt lgkmcnt(4)
	v_mfma_f32_32x32x16_bf16 v[80:95], v[116:119], v[130:133], v[96:111]
	ds_read_b128 v[116:119], v209 offset:96
	s_waitcnt lgkmcnt(4)
	v_mfma_f32_32x32x16_bf16 v[64:79], v[120:123], v[134:137], v[64:79]
	ds_read_b128 v[120:123], v209 offset:12896
	s_waitcnt lgkmcnt(4)
	v_mfma_f32_32x32x16_bf16 v[80:95], v[124:127], v[134:137], v[80:95]
	ds_read_b128 v[124:127], v209 offset:128
	s_waitcnt lgkmcnt(4)
	v_mfma_f32_32x32x16_bf16 v[64:79], v[250:253], v[138:141], v[64:79]
	ds_read_b128 v[250:253], v209 offset:12928
	s_waitcnt lgkmcnt(4)
	v_mfma_f32_32x32x16_bf16 v[80:95], v[112:115], v[138:141], v[80:95]
	ds_read_b128 v[112:115], v209 offset:160
	s_waitcnt lgkmcnt(4)
	v_mfma_f32_32x32x16_bf16 v[64:79], v[116:119], v[142:145], v[64:79]
	ds_read_b128 v[116:119], v209 offset:12960
	s_waitcnt lgkmcnt(4)
	v_mfma_f32_32x32x16_bf16 v[80:95], v[120:123], v[142:145], v[80:95]
	ds_read_b128 v[120:123], v209 offset:192
	s_waitcnt lgkmcnt(4)
	v_mfma_f32_32x32x16_bf16 v[64:79], v[124:127], v[146:149], v[64:79]
	ds_read_b128 v[124:127], v209 offset:12992
	s_waitcnt lgkmcnt(4)
	v_mfma_f32_32x32x16_bf16 v[80:95], v[250:253], v[146:149], v[80:95]
	ds_read_b128 v[250:253], v209 offset:224
	s_waitcnt lgkmcnt(4)
	v_mfma_f32_32x32x16_bf16 v[64:79], v[112:115], v[150:153], v[64:79]
	ds_read_b128 v[112:115], v209 offset:13024
	s_waitcnt lgkmcnt(4)
	v_mfma_f32_32x32x16_bf16 v[80:95], v[116:119], v[150:153], v[80:95]
	ds_read_b128 v[116:119], v209 offset:256
	s_waitcnt lgkmcnt(4)
	v_mfma_f32_32x32x16_bf16 v[64:79], v[120:123], v[154:157], v[64:79]
	ds_read_b128 v[120:123], v209 offset:13056
	s_waitcnt lgkmcnt(4)
	v_mfma_f32_32x32x16_bf16 v[80:95], v[124:127], v[154:157], v[80:95]
	ds_read_b128 v[124:127], v209 offset:288
	s_waitcnt lgkmcnt(4)
	v_mfma_f32_32x32x16_bf16 v[64:79], v[250:253], v[158:161], v[64:79]
	ds_read_b128 v[250:253], v209 offset:13088
	s_waitcnt lgkmcnt(4)
	v_mfma_f32_32x32x16_bf16 v[80:95], v[112:115], v[158:161], v[80:95]
	ds_read_b128 v[112:115], v209 offset:320
	s_waitcnt lgkmcnt(4)
	v_mfma_f32_32x32x16_bf16 v[64:79], v[116:119], v[162:165], v[64:79]
	ds_read_b128 v[116:119], v209 offset:13120
	s_waitcnt lgkmcnt(4)
	v_mfma_f32_32x32x16_bf16 v[80:95], v[120:123], v[162:165], v[80:95]
	ds_read_b128 v[120:123], v209 offset:352
	s_waitcnt lgkmcnt(4)
	v_mfma_f32_32x32x16_bf16 v[64:79], v[124:127], v[166:169], v[64:79]
	ds_read_b128 v[124:127], v209 offset:13152
	s_waitcnt lgkmcnt(4)
	v_mfma_f32_32x32x16_bf16 v[80:95], v[250:253], v[166:169], v[80:95]
	s_waitcnt lgkmcnt(3)
	v_mfma_f32_32x32x16_bf16 v[64:79], v[112:115], v[170:173], v[64:79]
	s_waitcnt lgkmcnt(2)
	v_mfma_f32_32x32x16_bf16 v[80:95], v[116:119], v[170:173], v[80:95]
	s_waitcnt lgkmcnt(1)
	v_mfma_f32_32x32x16_bf16 v[64:79], v[120:123], v[174:177], v[64:79]
	s_waitcnt lgkmcnt(0)
	v_mfma_f32_32x32x16_bf16 v[80:95], v[124:127], v[174:177], v[80:95]
	ds_read_b128 v[112:115], v219 offset:0
	ds_read_b128 v[116:119], v219 offset:4608
	ds_read_b128 v[120:123], v219 offset:9216
	s_cmp_eq_u32 s55, 0
	s_cselect_b32 s31, 0xff7fffff, 0
	s_nop 5
	v_max3_f32 v209, v64, v65, v66
	v_max3_f32 v211, v67, v68, v69
	v_max3_f32 v209, v209, v70, v71
	v_max3_f32 v211, v211, v72, v73
	v_max3_f32 v209, v209, v74, v75
	v_max3_f32 v211, v211, v76, v77
	v_max3_f32 v209, v209, v78, v79
	v_max3_f32 v213, v80, v81, v82
	v_max3_f32 v215, v83, v84, v85
	v_max3_f32 v213, v213, v86, v87
	v_max3_f32 v215, v215, v88, v89
	v_max3_f32 v213, v213, v90, v91
	v_max3_f32 v215, v215, v92, v93
	v_max3_f32 v213, v213, v94, v95
	v_max3_f32 v209, v209, v211, v213
	v_max_f32_e32 v209, v209, v215
	v_mov_b32_e32 v211, v209
	s_nop 1
	v_permlane32_swap_b32_e32 v209, v211
	v_max_f32_e32 v217, v209, v211
	v_cmp_lt_f32_e32 vcc, s58, v217
	s_cmp_eq_u32 s55, 0
	s_cbranch_scc1 .Latt_mla_rare
	s_cbranch_vccz .Latt_mla_norescale
.Latt_mla_rare:
	v_max_f32_e32 v211, s31, v217
	v_max_f32_e32 v213, 0, v211
	v_add_f32_e32 v207, v207, v211
	v_exp_f32_e64 v250, -v213
	v_sub_f32_e32 v96, v96, v211
	v_mov_b32_e32 v97, v96
	v_mov_b32_e32 v98, v96
	v_mov_b32_e32 v99, v96
	v_mov_b32_e32 v100, v96
	v_mov_b32_e32 v101, v96
	v_mov_b32_e32 v102, v96
	v_mov_b32_e32 v103, v96
	v_mov_b32_e32 v104, v96
	v_mov_b32_e32 v105, v96
	v_mov_b32_e32 v106, v96
	v_mov_b32_e32 v107, v96
	v_mov_b32_e32 v108, v96
	v_mov_b32_e32 v109, v96
	v_mov_b32_e32 v110, v96
	v_mov_b32_e32 v111, v96
	v_sub_f32_e32 v64, v64, v211
	v_sub_f32_e32 v65, v65, v211
	v_sub_f32_e32 v66, v66, v211
	v_sub_f32_e32 v67, v67, v211
	v_sub_f32_e32 v68, v68, v211
	v_sub_f32_e32 v69, v69, v211
	v_sub_f32_e32 v70, v70, v211
	v_sub_f32_e32 v71, v71, v211
	v_sub_f32_e32 v72, v72, v211
	v_sub_f32_e32 v73, v73, v211
	v_sub_f32_e32 v74, v74, v211
	v_sub_f32_e32 v75, v75, v211
	v_sub_f32_e32 v76, v76, v211
	v_sub_f32_e32 v77, v77, v211
	v_sub_f32_e32 v78, v78, v211
	v_sub_f32_e32 v79, v79, v211
	v_sub_f32_e32 v80, v80, v211
	v_sub_f32_e32 v81, v81, v211
	v_sub_f32_e32 v82, v82, v211
	v_sub_f32_e32 v83, v83, v211
	v_sub_f32_e32 v84, v84, v211
	v_sub_f32_e32 v85, v85, v211
	v_sub_f32_e32 v86, v86, v211
	v_sub_f32_e32 v87, v87, v211
	v_sub_f32_e32 v88, v88, v211
	v_sub_f32_e32 v89, v89, v211
	v_sub_f32_e32 v90, v90, v211
	v_sub_f32_e32 v91, v91, v211
	v_sub_f32_e32 v92, v92, v211
	v_sub_f32_e32 v93, v93, v211
	v_sub_f32_e32 v94, v94, v211
	v_sub_f32_e32 v95, v95, v211
	v_mul_f32_e32 v205, v205, v250
	v_pk_mul_f32 v[48:49], v[48:49], v[250:251] op_sel_hi:[1,0]
	v_pk_mul_f32 v[50:51], v[50:51], v[250:251] op_sel_hi:[1,0]
	v_pk_mul_f32 v[52:53], v[52:53], v[250:251] op_sel_hi:[1,0]
	v_pk_mul_f32 v[54:55], v[54:55], v[250:251] op_sel_hi:[1,0]
	v_pk_mul_f32 v[56:57], v[56:57], v[250:251] op_sel_hi:[1,0]
	v_pk_mul_f32 v[58:59], v[58:59], v[250:251] op_sel_hi:[1,0]
	v_pk_mul_f32 v[60:61], v[60:61], v[250:251] op_sel_hi:[1,0]
	v_pk_mul_f32 v[62:63], v[62:63], v[250:251] op_sel_hi:[1,0]
	v_pk_mul_f32 v[32:33], v[32:33], v[250:251] op_sel_hi:[1,0]
	v_pk_mul_f32 v[34:35], v[34:35], v[250:251] op_sel_hi:[1,0]
	v_pk_mul_f32 v[36:37], v[36:37], v[250:251] op_sel_hi:[1,0]
	v_pk_mul_f32 v[38:39], v[38:39], v[250:251] op_sel_hi:[1,0]
	v_pk_mul_f32 v[40:41], v[40:41], v[250:251] op_sel_hi:[1,0]
	v_pk_mul_f32 v[42:43], v[42:43], v[250:251] op_sel_hi:[1,0]
	v_pk_mul_f32 v[44:45], v[44:45], v[250:251] op_sel_hi:[1,0]
	v_pk_mul_f32 v[46:47], v[46:47], v[250:251] op_sel_hi:[1,0]
	v_pk_mul_f32 v[16:17], v[16:17], v[250:251] op_sel_hi:[1,0]
	v_pk_mul_f32 v[18:19], v[18:19], v[250:251] op_sel_hi:[1,0]
	v_pk_mul_f32 v[20:21], v[20:21], v[250:251] op_sel_hi:[1,0]
	v_pk_mul_f32 v[22:23], v[22:23], v[250:251] op_sel_hi:[1,0]
	v_pk_mul_f32 v[24:25], v[24:25], v[250:251] op_sel_hi:[1,0]
	v_pk_mul_f32 v[26:27], v[26:27], v[250:251] op_sel_hi:[1,0]
	v_pk_mul_f32 v[28:29], v[28:29], v[250:251] op_sel_hi:[1,0]
	v_pk_mul_f32 v[30:31], v[30:31], v[250:251] op_sel_hi:[1,0]
	v_pk_mul_f32 v[0:1], v[0:1], v[250:251] op_sel_hi:[1,0]
	v_pk_mul_f32 v[2:3], v[2:3], v[250:251] op_sel_hi:[1,0]
	v_pk_mul_f32 v[4:5], v[4:5], v[250:251] op_sel_hi:[1,0]
	v_pk_mul_f32 v[6:7], v[6:7], v[250:251] op_sel_hi:[1,0]
	v_pk_mul_f32 v[8:9], v[8:9], v[250:251] op_sel_hi:[1,0]
	v_pk_mul_f32 v[10:11], v[10:11], v[250:251] op_sel_hi:[1,0]
	v_pk_mul_f32 v[12:13], v[12:13], v[250:251] op_sel_hi:[1,0]
	v_pk_mul_f32 v[14:15], v[14:15], v[250:251] op_sel_hi:[1,0]
.Latt_mla_norescale:
	v_exp_f32_e32 v64, v64
	v_exp_f32_e32 v65, v65
	v_exp_f32_e32 v66, v66
	v_exp_f32_e32 v67, v67
	v_exp_f32_e32 v68, v68
	v_exp_f32_e32 v69, v69
	v_exp_f32_e32 v70, v70
	v_exp_f32_e32 v71, v71
	v_cvt_pk_bf16_f32 v124, v64, v65
	v_cvt_pk_bf16_f32 v125, v66, v67
	v_cvt_pk_bf16_f32 v126, v68, v69
	v_cvt_pk_bf16_f32 v127, v70, v71
	s_waitcnt lgkmcnt(2)
	s_nop 0
	v_mfma_f32_32x32x16_bf16 v[48:63], v[112:115], v[124:127], v[48:63]
	ds_read_b128 v[112:115], v219 offset:13824
	v_exp_f32_e32 v72, v72
	v_exp_f32_e32 v73, v73
	v_exp_f32_e32 v74, v74
	v_exp_f32_e32 v75, v75
	s_waitcnt lgkmcnt(2)
	v_mfma_f32_32x32x16_bf16 v[32:47], v[116:119], v[124:127], v[32:47]
	ds_read_b128 v[116:119], v219 offset:32
	v_cvt_pk_bf16_f32 v250, v72, v73
	v_exp_f32_e32 v76, v76
	v_exp_f32_e32 v77, v77
	v_cvt_pk_bf16_f32 v251, v74, v75
	s_waitcnt lgkmcnt(2)
	v_mfma_f32_32x32x16_bf16 v[16:31], v[120:123], v[124:127], v[16:31]
	ds_read_b128 v[120:123], v219 offset:4640
	v_exp_f32_e32 v78, v78
	v_exp_f32_e32 v79, v79
	v_cvt_pk_bf16_f32 v252, v76, v77
	v_cvt_pk_bf16_f32 v253, v78, v79
	s_waitcnt lgkmcnt(2)
	v_mfma_f32_32x32x16_bf16 v[0:15], v[112:115], v[124:127], v[0:15]
	ds_read_b128 v[112:115], v219 offset:9248
	v_add_f32_e32 v209, v64, v68
	v_add_f32_e32 v211, v65, v69
	v_add_f32_e32 v213, v66, v70
	v_add_f32_e32 v215, v67, v71
	s_waitcnt lgkmcnt(2)
	v_mfma_f32_32x32x16_bf16 v[48:63], v[116:119], v[250:253], v[48:63]
	ds_read_b128 v[64:67], v219 offset:13856
	ds_read_b128 v[68:71], v219 offset:64
	v_exp_f32_e32 v80, v80
	v_exp_f32_e32 v81, v81
	v_exp_f32_e32 v82, v82
	v_exp_f32_e32 v83, v83
	v_cvt_pk_bf16_f32 v124, v80, v81
	s_waitcnt lgkmcnt(3)
	v_mfma_f32_32x32x16_bf16 v[32:47], v[120:123], v[250:253], v[32:47]
	ds_read_b128 v[116:119], v219 offset:4672
	ds_read_b128 v[120:123], v219 offset:9280
	v_exp_f32_e32 v84, v84
	v_exp_f32_e32 v85, v85
	v_cvt_pk_bf16_f32 v125, v82, v83
	v_exp_f32_e32 v86, v86
	v_exp_f32_e32 v87, v87
	s_waitcnt lgkmcnt(4)
	v_mfma_f32_32x32x16_bf16 v[16:31], v[112:115], v[250:253], v[16:31]
	ds_read_b128 v[112:115], v219 offset:13888
	v_cvt_pk_bf16_f32 v126, v84, v85
	v_cvt_pk_bf16_f32 v127, v86, v87
	v_add_f32_e32 v209, v209, v72
	v_add_f32_e32 v211, v211, v73
	v_add_f32_e32 v213, v213, v74
	s_waitcnt lgkmcnt(4)
	v_mfma_f32_32x32x16_bf16 v[0:15], v[64:67], v[250:253], v[0:15]
	ds_read_b128 v[64:67], v219 offset:96
	v_add_f32_e32 v215, v215, v75
	v_add_f32_e32 v209, v209, v76
	v_add_f32_e32 v211, v211, v77
	v_add_f32_e32 v213, v213, v78
	v_add_f32_e32 v215, v215, v79
	s_waitcnt lgkmcnt(4)
	v_mfma_f32_32x32x16_bf16 v[48:63], v[68:71], v[124:127], v[48:63]
	ds_read_b128 v[72:75], v219 offset:4704
	ds_read_b128 v[76:79], v219 offset:9312
	v_exp_f32_e32 v88, v88
	v_exp_f32_e32 v89, v89
	v_exp_f32_e32 v90, v90
	v_exp_f32_e32 v91, v91
	v_cvt_pk_bf16_f32 v250, v88, v89
	s_waitcnt lgkmcnt(5)
	v_mfma_f32_32x32x16_bf16 v[32:47], v[116:119], v[124:127], v[32:47]
	ds_read_b128 v[68:71], v219 offset:13920
	v_exp_f32_e32 v92, v92
	v_exp_f32_e32 v93, v93
	v_cvt_pk_bf16_f32 v251, v90, v91
	v_exp_f32_e32 v94, v94
	v_exp_f32_e32 v95, v95
	s_waitcnt lgkmcnt(5)
	v_mfma_f32_32x32x16_bf16 v[16:31], v[120:123], v[124:127], v[16:31]
	v_cvt_pk_bf16_f32 v252, v92, v93
	v_cvt_pk_bf16_f32 v253, v94, v95
	v_add_f32_e32 v209, v209, v80
	v_add_f32_e32 v211, v211, v81
	v_add_f32_e32 v213, v213, v82
	s_waitcnt lgkmcnt(4)
	v_mfma_f32_32x32x16_bf16 v[0:15], v[112:115], v[124:127], v[0:15]
	v_add_f32_e32 v215, v215, v83
	v_add_f32_e32 v209, v209, v84
	v_add_f32_e32 v211, v211, v85
	v_add_f32_e32 v213, v213, v86
	v_add_f32_e32 v215, v215, v87
	s_waitcnt lgkmcnt(3)
	v_mfma_f32_32x32x16_bf16 v[48:63], v[64:67], v[250:253], v[48:63]
	v_add_f32_e32 v209, v209, v88
	v_add_f32_e32 v211, v211, v89
	s_waitcnt lgkmcnt(2)
	v_mfma_f32_32x32x16_bf16 v[32:47], v[72:75], v[250:253], v[32:47]
	v_add_f32_e32 v213, v213, v90
	v_add_f32_e32 v215, v215, v91
	s_waitcnt lgkmcnt(1)
	v_mfma_f32_32x32x16_bf16 v[16:31], v[76:79], v[250:253], v[16:31]
	v_add_f32_e32 v209, v209, v92
	v_add_f32_e32 v211, v211, v93
	s_waitcnt lgkmcnt(0)
	v_mfma_f32_32x32x16_bf16 v[0:15], v[68:71], v[250:253], v[0:15]
	v_add_f32_e32 v213, v213, v94
	v_add_f32_e32 v215, v215, v95
	v_add_f32_e32 v209, v209, v211
	v_add_f32_e32 v213, v213, v215
	v_add_f32_e32 v209, v209, v213
	v_add_f32_e32 v205, v205, v209
	s_and_b64 vcc, exec, s[60:61]
	s_cbranch_vccz .Latt_mla_w_n
	s_waitcnt vmcnt(0)
	s_branch .Latt_mla_w_d
.Latt_mla_w_n:
	s_waitcnt vmcnt(5)
.Latt_mla_w_d:
	s_waitcnt lgkmcnt(0)
	s_barrier
	s_add_i32 s30, s52, 1
	s_cmp_lg_u32 s52, 2
	s_cselect_b32 s57, s30, 0
	s_add_i32 s55, s55, 1
	s_add_i32 s49, s49, 64
	s_add_i32 s51, s51, 64
	s_cmp_eq_u32 s20, s55
	s_cbranch_scc1 .LBB0_153
	s_mov_b32 s56, s53
	s_mov_b32 s53, s52
	s_mov_b32 s52, s57
	s_branch .LBB0_178

.LBB0_200:
	s_add_i32 s30, s57, s42
	s_add_i32 m0, s30, 0x2000
	v_lshl_add_u64 v[250:251], s[62:63], 0, v[200:201]
	global_load_lds_dwordx4 v[250:251], off
	s_and_b64 vcc, exec, s[18:19]
	s_cbranch_vccz .LBB0_190
	s_branch .LBB0_191
